# chunk-attention K/V cache stream loads without nt (default cache policy)
# baseline (speedup 1.0000x reference)
.LBB0_1000:
	s_or_b64 exec, exec, s[8:9]
	s_mov_b64 s[6:7], s[0:1]
	s_waitcnt lgkmcnt(0)
	s_barrier
	s_load_dwordx2 s[6:7], s[6:7], 0x10
	s_mov_b64 s[8:9], s[0:1]
	s_load_dwordx2 s[8:9], s[8:9], 0x18
	s_mov_b64 s[12:13], s[0:1]
	v_readlane_b32 s18, v255, 23
	s_load_dwordx2 s[16:17], s[12:13], 0xb0
	v_readlane_b32 s19, v255, 24
	s_waitcnt lgkmcnt(0)
	s_add_u32 s10, s6, s18
	s_addc_u32 s11, s7, s19
	s_add_u32 s12, s8, s18
	v_readlane_b32 s6, v254, 33
	s_addc_u32 s13, s9, s19
	s_lshl_b32 s6, s6, 1
	v_readlane_b32 s7, v254, 34
	s_add_u32 s6, s16, s6
	v_readlane_b32 s8, v254, 31
	s_addc_u32 s7, s17, 0
	s_lshl_b32 s8, s8, 1
	v_mov_b32_e32 v95, v219
	s_add_u32 s6, s6, s8
	s_addc_u32 s7, s7, 0
	v_and_b32_e32 v9, 15, v95
	v_lshlrev_b32_e32 v96, 11, v9
	v_lshrrev_b32_e32 v2, 1, v95
	v_lshl_add_u64 v[0:1], s[6:7], 0, v[96:97]
	v_and_b32_e32 v96, 24, v2
	v_readfirstlane_b32 s8, v95
	v_lshl_add_u64 v[0:1], v[0:1], 0, v[96:97]
	s_mov_b64 s[6:7], 0x14a08000
	s_ashr_i32 s16, s8, 6
	v_lshl_add_u64 v[2:3], v[0:1], 0, s[6:7]
	s_mov_b32 s6, 0x14a08000
	v_add_co_u32_e32 v0, vcc, s6, v0
	s_lshl_b32 s6, s16, 4
	v_readlane_b32 s7, v252, 47
	s_add_i32 s6, s6, s7
	v_readlane_b32 s9, v254, 32
	s_ashr_i32 s7, s6, 31
	s_add_i32 s17, s6, 16
	s_lshl_b64 s[8:9], s[6:7], 16
	s_add_u32 s18, s10, s8
	v_bfe_u32 v241, v95, 2, 4
	v_addc_co_u32_e32 v1, vcc, 0, v1, vcc
	s_addc_u32 s19, s11, s9
	v_lshlrev_b32_e32 v96, 12, v9
	v_and_b32_e32 v8, 12, v241
	global_load_dwordx2 v[40:41], v[2:3], off offset:32
	global_load_dwordx2 v[42:43], v[2:3], off offset:64
	global_load_dwordx2 v[44:45], v[2:3], off offset:96
	global_load_dwordx2 v[46:47], v[2:3], off offset:128
	global_load_dwordx2 v[38:39], v[0:1], off
	global_load_dwordx2 v[48:49], v[2:3], off offset:160
	global_load_dwordx2 v[34:35], v[2:3], off offset:192
	global_load_dwordx2 v[36:37], v[2:3], off offset:224
	v_lshl_add_u64 v[0:1], s[18:19], 0, v[96:97]
	v_lshlrev_b32_e32 v2, 2, v8
	v_mov_b32_e32 v3, v97
	s_add_u32 s8, s12, s8
	v_lshl_add_u64 v[0:1], v[0:1], 0, v[2:3]
	s_addc_u32 s9, s13, s9
	global_load_dwordx4 v[114:117], v[0:1], off
	global_load_dwordx4 v[110:113], v[0:1], off offset:64
	global_load_dwordx4 v[106:109], v[0:1], off offset:128
	global_load_dwordx4 v[102:105], v[0:1], off offset:192
	global_load_dwordx4 v[90:93], v[0:1], off offset:256
	global_load_dwordx4 v[98:101], v[0:1], off offset:320
	global_load_dwordx4 v[86:89], v[0:1], off offset:384
	global_load_dwordx4 v[82:85], v[0:1], off offset:448
	v_lshlrev_b32_e32 v0, 4, v9
	v_mov_b32_e32 v1, v97
	v_lshl_add_u64 v[4:5], s[8:9], 0, v[0:1]
	v_lshlrev_b32_e32 v6, 12, v8
	v_mov_b32_e32 v7, v97
	v_lshl_add_u64 v[6:7], v[4:5], 0, v[6:7]
	v_add_co_u32_e32 v10, vcc, s30, v6
	v_mov_b32_e32 v12, 0xc00
	s_nop 0
	v_addc_co_u32_e32 v11, vcc, 0, v7, vcc
	global_load_dwordx4 v[58:61], v[6:7], off
	global_load_dwordx4 v[54:57], v[6:7], off offset:256
	v_add_co_u32_e32 v6, vcc, s33, v6
	v_lshl_or_b32 v94, v241, 10, v12
	s_nop 0
	v_addc_co_u32_e32 v7, vcc, 0, v7, vcc
	v_lshlrev_b32_e32 v12, 2, v94
	v_mov_b32_e32 v13, v97
	global_load_dwordx4 v[66:69], v[6:7], off
	global_load_dwordx4 v[62:65], v[6:7], off offset:256
	v_lshl_add_u64 v[4:5], v[4:5], 0, v[12:13]
	global_load_dwordx4 v[74:77], v[10:11], off offset:256
	global_load_dwordx4 v[70:73], v[4:5], off
	global_load_dwordx4 v[78:81], v[6:7], off offset:-4096
	global_load_dwordx4 v[50:53], v[4:5], off offset:256
	v_lshl_add_u64 v[4:5], s[10:11], 0, v[96:97]
	s_lshl_b32 s9, s16, 10
	v_readlane_b32 s10, v254, 22
	v_and_b32_e32 v238, 48, v95
	s_add_i32 s9, s10, s9
	v_mov_b32_e32 v151, 0
	v_lshlrev_b32_e32 v222, 10, v9
	v_and_b32_e32 v239, 63, v95
	v_lshlrev_b32_e32 v220, 2, v9
	v_lshlrev_b32_e32 v218, 10, v8
	s_or_b32 s8, s6, 1
	v_lshl_add_u64 v[224:225], s[12:13], 0, v[0:1]
	v_lshl_add_u64 v[226:227], v[4:5], 0, v[2:3]
	s_or_b32 s7, s6, 15
	v_add_u32_e32 v243, s9, v238
	v_mov_b32_e32 v150, 0xf149f2ca
	v_mov_b32_e32 v126, 0
	v_mov_b32_e32 v127, v151
	v_mov_b32_e32 v128, v151
	v_mov_b32_e32 v129, v151
	v_mov_b32_e32 v130, 0
	v_mov_b32_e32 v131, v151
	v_mov_b32_e32 v132, v151
	v_mov_b32_e32 v133, v151
	v_mov_b32_e32 v134, 0
	v_mov_b32_e32 v135, v151
	v_mov_b32_e32 v136, v151
	v_mov_b32_e32 v137, v151
	v_mov_b32_e32 v122, 0
	v_mov_b32_e32 v123, v151
	v_mov_b32_e32 v124, v151
	v_mov_b32_e32 v125, v151
	v_mov_b32_e32 v138, 0
	v_mov_b32_e32 v139, v151
	v_mov_b32_e32 v140, v151
	v_mov_b32_e32 v141, v151
	v_mov_b32_e32 v142, 0
	v_mov_b32_e32 v143, v151
	v_mov_b32_e32 v144, v151
	v_mov_b32_e32 v145, v151
	v_mov_b32_e32 v146, 0
	v_mov_b32_e32 v147, v151
	v_mov_b32_e32 v148, v151
	v_mov_b32_e32 v149, v151
	v_mov_b32_e32 v118, 0
	v_mov_b32_e32 v119, v151
	v_mov_b32_e32 v120, v151
	v_mov_b32_e32 v121, v151
	s_branch .LBB0_1003

.LBB0_1003:
	s_nop 6
	v_mov_b32_e32 v20, v120
	v_mov_b32_e32 v19, v119
	v_mov_b32_e32 v18, v118
	v_mov_b32_e32 v17, v149
	v_mov_b32_e32 v16, v148
	v_mov_b32_e32 v15, v147
	v_mov_b32_e32 v14, v146
	v_mov_b32_e32 v3, v145
	v_mov_b32_e32 v2, v144
	v_mov_b32_e32 v1, v143
	v_mov_b32_e32 v0, v142
	v_mov_b32_e32 v13, v141
	v_mov_b32_e32 v12, v140
	v_mov_b32_e32 v11, v139
	v_mov_b32_e32 v10, v138
	v_mov_b32_e32 v33, v125
	v_mov_b32_e32 v32, v124
	v_mov_b32_e32 v31, v123
	v_mov_b32_e32 v30, v122
	v_mov_b32_e32 v29, v137
	v_mov_b32_e32 v28, v136
	v_mov_b32_e32 v27, v135
	v_mov_b32_e32 v26, v134
	v_mov_b32_e32 v7, v133
	v_mov_b32_e32 v6, v132
	v_mov_b32_e32 v5, v131
	v_mov_b32_e32 v4, v130
	v_mov_b32_e32 v25, v129
	v_mov_b32_e32 v24, v128
	v_mov_b32_e32 v23, v127
	v_mov_b32_e32 v22, v126
	v_mov_b32_e32 v240, v151
	v_mov_b32_e32 v242, v150
	v_mov_b32_e32 v21, v121
	s_cmp_lt_i32 s6, s17
	s_mov_b64 s[10:11], -1
	s_cbranch_scc0 .LBB0_1002
	s_ashr_i32 s9, s8, 31
	s_lshl_b64 s[8:9], s[8:9], 16
	v_lshl_add_u64 v[118:119], v[226:227], 0, s[8:9]
	global_load_dwordx4 v[178:181], v[118:119], off
	global_load_dwordx4 v[174:177], v[118:119], off offset:64
	global_load_dwordx4 v[170:173], v[118:119], off offset:128
	global_load_dwordx4 v[166:169], v[118:119], off offset:192
	global_load_dwordx4 v[162:165], v[118:119], off offset:256
	global_load_dwordx4 v[158:161], v[118:119], off offset:320
	global_load_dwordx4 v[154:157], v[118:119], off offset:384
	global_load_dwordx4 v[150:153], v[118:119], off offset:448
	v_lshl_add_u64 v[118:119], v[224:225], 0, s[8:9]
	v_lshlrev_b32_e32 v96, 2, v218
	v_lshl_add_u64 v[120:121], v[118:119], 0, v[96:97]
	v_add_co_u32_e32 v122, vcc, s30, v120
	global_load_dwordx4 v[142:145], v[120:121], off
	global_load_dwordx4 v[134:137], v[120:121], off offset:256
	v_addc_co_u32_e32 v123, vcc, 0, v121, vcc
	v_add_co_u32_e32 v120, vcc, s33, v120
	v_lshlrev_b32_e32 v210, 2, v94
	v_mov_b32_e32 v211, v97
	v_addc_co_u32_e32 v121, vcc, 0, v121, vcc
	v_lshl_add_u64 v[118:119], v[118:119], 0, v[210:211]
	global_load_dwordx4 v[130:133], v[120:121], off
	global_load_dwordx4 v[126:129], v[120:121], off offset:256
	global_load_dwordx4 v[138:141], v[122:123], off offset:256
	s_nop 0
	global_load_dwordx4 v[122:125], v[118:119], off
	global_load_dwordx4 v[146:149], v[120:121], off offset:-4096
	s_nop 0
	global_load_dwordx4 v[118:121], v[118:119], off offset:256
	s_waitcnt vmcnt(31)
	v_cvt_pk_bf16_f32 v114, v114, v115
	v_cvt_pk_bf16_f32 v115, v116, v117
	s_waitcnt vmcnt(30)
	v_cvt_pk_bf16_f32 v116, v110, v111
	v_cvt_pk_bf16_f32 v117, v112, v113
	s_waitcnt vmcnt(29)
	v_cvt_pk_bf16_f32 v106, v106, v107
	v_cvt_pk_bf16_f32 v107, v108, v109
	s_waitcnt vmcnt(28)
	v_cvt_pk_bf16_f32 v108, v102, v103
	v_cvt_pk_bf16_f32 v109, v104, v105
	v_mfma_f32_16x16x32_bf16 v[110:113], v[114:117], v[38:41], 0
	s_waitcnt vmcnt(27)
	v_cvt_pk_bf16_f32 v90, v90, v91
	v_cvt_pk_bf16_f32 v91, v92, v93
	s_waitcnt vmcnt(26)
	v_cvt_pk_bf16_f32 v92, v98, v99
	v_cvt_pk_bf16_f32 v93, v100, v101
	v_mfma_f32_16x16x32_bf16 v[102:105], v[106:109], v[42:45], v[110:113]
	s_waitcnt vmcnt(25)
	v_cvt_pk_bf16_f32 v86, v86, v87
	v_cvt_pk_bf16_f32 v87, v88, v89
	s_waitcnt vmcnt(24)
	v_cvt_pk_bf16_f32 v88, v82, v83
	v_cvt_pk_bf16_f32 v89, v84, v85
	v_mfma_f32_16x16x32_bf16 v[90:93], v[90:93], v[46:49], v[102:105]
	ds_read_b128 v[82:85], v243
	v_mfma_f32_16x16x32_bf16 v[86:89], v[86:89], v[34:37], v[90:93]
	s_waitcnt lgkmcnt(0)
	s_nop 6
	v_fmamk_f32 v186, v86, 0x3e0293ee, v82
	v_fmamk_f32 v82, v88, 0x3e0293ee, v84
	v_fmac_f32_e32 v85, 0x3e0293ee, v89
	v_fmamk_f32 v83, v87, 0x3e0293ee, v83
	v_max_f32_e32 v84, v82, v85
	v_max3_f32 v84, v186, v83, v84
	v_mov_b32_e32 v86, v84
	s_nop 1
	v_permlane16_swap_b32_e32 v84, v86
	v_max_f32_e32 v86, v86, v86
	v_max_f32_e32 v84, v84, v84
	v_max_f32_e32 v84, v84, v86
	v_mov_b32_e32 v86, v84
	s_nop 1
	v_permlane32_swap_b32_e32 v84, v86
	v_max3_f32 v244, v242, v84, v86
	v_sub_f32_e32 v84, v242, v244
	v_exp_f32_e32 v228, v84
	s_nop 0
	v_cmp_neq_f32_e32 vcc, 1.0, v228
	s_cbranch_vccz .LBB0_1009
	v_pk_mul_f32 v[88:89], v[24:25], v[228:229] op_sel_hi:[1,0]
	v_pk_mul_f32 v[86:87], v[22:23], v[228:229] op_sel_hi:[1,0]
	v_pk_mul_f32 v[92:93], v[6:7], v[228:229] op_sel_hi:[1,0]
	v_pk_mul_f32 v[90:91], v[4:5], v[228:229] op_sel_hi:[1,0]
	v_pk_mul_f32 v[100:101], v[28:29], v[228:229] op_sel_hi:[1,0]
	v_pk_mul_f32 v[98:99], v[26:27], v[228:229] op_sel_hi:[1,0]
	v_pk_mul_f32 v[104:105], v[32:33], v[228:229] op_sel_hi:[1,0]
	v_pk_mul_f32 v[102:103], v[30:31], v[228:229] op_sel_hi:[1,0]
	v_pk_mul_f32 v[108:109], v[12:13], v[228:229] op_sel_hi:[1,0]
	v_pk_mul_f32 v[106:107], v[10:11], v[228:229] op_sel_hi:[1,0]
	v_pk_mul_f32 v[112:113], v[2:3], v[228:229] op_sel_hi:[1,0]
	v_pk_mul_f32 v[110:111], v[0:1], v[228:229] op_sel_hi:[1,0]
	v_pk_mul_f32 v[116:117], v[16:17], v[228:229] op_sel_hi:[1,0]
	v_pk_mul_f32 v[114:115], v[14:15], v[228:229] op_sel_hi:[1,0]
	v_pk_mul_f32 v[184:185], v[20:21], v[228:229] op_sel_hi:[1,0]
	v_pk_mul_f32 v[182:183], v[18:19], v[228:229] op_sel_hi:[1,0]
	s_cbranch_execnz .LBB0_1007

.LBB0_1007:
	v_sub_f32_e32 v84, v186, v244
	v_exp_f32_e32 v245, v84
	v_sub_f32_e32 v83, v83, v244
	v_exp_f32_e32 v246, v83
	s_add_i32 s9, s6, 2
	s_waitcnt vmcnt(23)
	v_mfma_f32_16x16x4_f32 v[86:89], v58, v245, v[86:89]
	s_min_i32 s10, s9, s7
	s_ashr_i32 s11, s10, 31
	s_lshl_b64 s[10:11], s[10:11], 16
	v_mov_b32_e32 v211, v97
	s_waitcnt vmcnt(15)
	v_cvt_pk_bf16_f32 v178, v178, v179
	v_cvt_pk_bf16_f32 v179, v180, v181
	s_waitcnt vmcnt(14)
	v_cvt_pk_bf16_f32 v180, v174, v175
	v_mfma_f32_16x16x4_f32 v[90:93], v59, v245, v[90:93]
	v_cvt_pk_bf16_f32 v181, v176, v177
	s_waitcnt vmcnt(13)
	v_cvt_pk_bf16_f32 v170, v170, v171
	v_cvt_pk_bf16_f32 v171, v172, v173
	s_waitcnt vmcnt(12)
	v_cvt_pk_bf16_f32 v172, v166, v167
	v_cvt_pk_bf16_f32 v173, v168, v169
	s_waitcnt vmcnt(11)
	v_cvt_pk_bf16_f32 v162, v162, v163
	v_cvt_pk_bf16_f32 v163, v164, v165
	v_mfma_f32_16x16x4_f32 v[98:101], v60, v245, v[98:101]
	s_waitcnt vmcnt(10)
	v_cvt_pk_bf16_f32 v164, v158, v159
	v_cvt_pk_bf16_f32 v165, v160, v161
	s_waitcnt vmcnt(9)
	v_cvt_pk_bf16_f32 v154, v154, v155
	v_cvt_pk_bf16_f32 v155, v156, v157
	s_waitcnt vmcnt(8)
	v_cvt_pk_bf16_f32 v156, v150, v151
	v_cvt_pk_bf16_f32 v157, v152, v153
	v_mfma_f32_16x16x4_f32 v[58:61], v61, v245, v[102:105]
	v_mfma_f32_16x16x4_f32 v[102:105], v54, v245, v[106:109]
	v_mfma_f32_16x16x4_f32 v[106:109], v55, v245, v[110:113]
	v_mfma_f32_16x16x4_f32 v[110:113], v56, v245, v[114:117]
	v_mfma_f32_16x16x4_f32 v[54:57], v57, v245, v[182:185]
	v_mfma_f32_16x16x4_f32 v[86:89], v78, v246, v[86:89]
	v_mfma_f32_16x16x4_f32 v[90:93], v79, v246, v[90:93]
	v_mfma_f32_16x16x4_f32 v[98:101], v80, v246, v[98:101]
	v_mfma_f32_16x16x4_f32 v[58:61], v81, v246, v[58:61]
	v_mfma_f32_16x16x4_f32 v[78:81], v74, v246, v[102:105]
	v_sub_f32_e32 v74, v82, v244
	v_exp_f32_e32 v247, v74
	v_mfma_f32_16x16x4_f32 v[102:105], v75, v246, v[106:109]
	v_mfma_f32_16x16x4_f32 v[54:57], v77, v246, v[54:57]
	v_mfma_f32_16x16x4_f32 v[106:109], v76, v246, v[110:113]
	v_mfma_f32_16x16x4_f32 v[74:77], v66, v247, v[86:89]
	v_mfma_f32_16x16x4_f32 v[86:89], v67, v247, v[90:93]
	v_mfma_f32_16x16x4_f32 v[90:93], v68, v247, v[98:101]
	v_mfma_f32_16x16x4_f32 v[58:61], v69, v247, v[58:61]
	v_mfma_f32_16x16x4_f32 v[66:69], v62, v247, v[78:81]
	v_mfma_f32_16x16x4_f32 v[78:81], v63, v247, v[102:105]
	v_mfma_f32_16x16x4_f32 v[212:215], v65, v247, v[54:57]
	s_nop 1
	v_sub_f32_e32 v54, v85, v244
	v_exp_f32_e32 v248, v54
	v_lshl_add_u64 v[54:55], v[226:227], 0, s[10:11]
	global_load_dwordx4 v[114:117], v[54:55], off
	global_load_dwordx4 v[110:113], v[54:55], off offset:64
	v_mfma_f32_16x16x4_f32 v[206:209], v64, v247, v[106:109]
	v_mfma_f32_16x16x4_f32 v[194:197], v70, v248, v[74:77]
	v_mfma_f32_16x16x4_f32 v[190:193], v71, v248, v[86:89]
	v_lshl_add_u64 v[70:71], v[224:225], 0, s[10:11]
	v_lshl_add_u64 v[230:231], v[70:71], 0, v[210:211]
	v_mfma_f32_16x16x4_f32 v[198:201], v50, v248, v[66:69]
	v_mfma_f32_16x16x4_f32 v[202:205], v51, v248, v[78:81]
	v_lshl_add_u64 v[50:51], v[70:71], 0, v[96:97]
	v_mfma_f32_16x16x4_f32 v[186:189], v72, v248, v[90:93]
	global_load_dwordx4 v[106:109], v[54:55], off offset:128
	global_load_dwordx4 v[102:105], v[54:55], off offset:192
	global_load_dwordx4 v[90:93], v[54:55], off offset:256
	global_load_dwordx4 v[98:101], v[54:55], off offset:320
	global_load_dwordx4 v[86:89], v[54:55], off offset:384
	global_load_dwordx4 v[82:85], v[54:55], off offset:448
	v_add_co_u32_e32 v72, vcc, s30, v50
	v_mfma_f32_16x16x4_f32 v[182:185], v73, v248, v[58:61]
	s_nop 0
	v_addc_co_u32_e32 v73, vcc, 0, v51, vcc
	global_load_dwordx4 v[58:61], v[50:51], off
	global_load_dwordx4 v[54:57], v[50:51], off offset:256
	v_add_co_u32_e32 v50, vcc, s33, v50
	s_nop 1
	v_addc_co_u32_e32 v51, vcc, 0, v51, vcc
	v_mfma_f32_16x16x4_f32 v[206:209], v52, v248, v[206:209]
	global_load_dwordx4 v[66:69], v[50:51], off
	global_load_dwordx4 v[62:65], v[50:51], off offset:256
	global_load_dwordx4 v[74:77], v[72:73], off offset:256
	s_nop 0
	global_load_dwordx4 v[70:73], v[230:231], off
	v_mfma_f32_16x16x4_f32 v[210:213], v53, v248, v[212:215]
	global_load_dwordx4 v[78:81], v[50:51], off offset:-4096
	s_nop 0
	global_load_dwordx4 v[50:53], v[230:231], off offset:256
	ds_read_b128 v[150:153], v243 offset:64
	v_mfma_f32_16x16x32_bf16 v[166:169], v[178:181], v[38:41], 0
	v_mfma_f32_16x16x32_bf16 v[158:161], v[170:173], v[42:45], v[166:169]
	v_mfma_f32_16x16x32_bf16 v[158:161], v[162:165], v[46:49], v[158:161]
	v_mfma_f32_16x16x32_bf16 v[156:159], v[154:157], v[34:37], v[158:161]
	s_waitcnt lgkmcnt(0)
	s_nop 6
	v_fmamk_f32 v154, v157, 0x3e0293ee, v151
	v_fmamk_f32 v151, v158, 0x3e0293ee, v152
	v_fmac_f32_e32 v153, 0x3e0293ee, v159
	v_fmamk_f32 v155, v156, 0x3e0293ee, v150
	v_max_f32_e32 v96, v151, v153
	v_max3_f32 v96, v155, v154, v96
	v_mov_b32_e32 v150, v96
	s_nop 1
	v_permlane16_swap_b32_e32 v96, v150
	v_max_f32_e32 v150, v150, v150
	v_max_f32_e32 v96, v96, v96
	v_max_f32_e32 v96, v96, v150
	v_mov_b32_e32 v150, v96
	s_nop 1
	v_permlane32_swap_b32_e32 v96, v150
	v_max3_f32 v150, v244, v96, v150
	v_sub_f32_e32 v96, v244, v150
	v_exp_f32_e32 v96, v96
	s_nop 0
	v_cmp_neq_f32_e32 vcc, 1.0, v96
	s_cbranch_vccz .LBB0_1001
	v_pk_mul_f32 v[196:197], v[196:197], v[96:97] op_sel_hi:[1,0]
	v_pk_mul_f32 v[194:195], v[194:195], v[96:97] op_sel_hi:[1,0]
	v_pk_mul_f32 v[192:193], v[192:193], v[96:97] op_sel_hi:[1,0]
	v_pk_mul_f32 v[190:191], v[190:191], v[96:97] op_sel_hi:[1,0]
	v_pk_mul_f32 v[188:189], v[188:189], v[96:97] op_sel_hi:[1,0]
	v_pk_mul_f32 v[186:187], v[186:187], v[96:97] op_sel_hi:[1,0]
	v_pk_mul_f32 v[184:185], v[184:185], v[96:97] op_sel_hi:[1,0]
	v_pk_mul_f32 v[182:183], v[182:183], v[96:97] op_sel_hi:[1,0]
	v_pk_mul_f32 v[200:201], v[200:201], v[96:97] op_sel_hi:[1,0]
	v_pk_mul_f32 v[198:199], v[198:199], v[96:97] op_sel_hi:[1,0]
	v_pk_mul_f32 v[204:205], v[204:205], v[96:97] op_sel_hi:[1,0]
	v_pk_mul_f32 v[202:203], v[202:203], v[96:97] op_sel_hi:[1,0]
	v_pk_mul_f32 v[208:209], v[208:209], v[96:97] op_sel_hi:[1,0]
	v_pk_mul_f32 v[206:207], v[206:207], v[96:97] op_sel_hi:[1,0]
	v_pk_mul_f32 v[212:213], v[212:213], v[96:97] op_sel_hi:[1,0]
	v_pk_mul_f32 v[210:211], v[210:211], v[96:97] op_sel_hi:[1,0]
	s_branch .LBB0_1001

.LBB0_1010:
	s_cmp_eq_u32 s16, 7
	v_readlane_b32 s8, v252, 48
	s_cselect_b64 s[6:7], -1, 0
	v_readlane_b32 s9, v252, 49
	s_and_b64 s[6:7], s[8:9], s[6:7]
	s_and_b64 vcc, exec, s[6:7]
	s_cbranch_vccz .LBB0_1022
	v_readlane_b32 s6, v254, 31
	v_readlane_b32 s7, v254, 32
	s_lshl_b32 s6, s6, 2
	v_readlane_b32 s8, v255, 21
	v_readlane_b32 s9, v255, 22
	s_add_u32 s7, s22, s8
	s_addc_u32 s8, s23, s9
	s_add_u32 s6, s7, s6
	s_addc_u32 s7, s8, 0
	v_lshlrev_b32_e32 v96, 2, v222
	s_waitcnt vmcnt(0)
	v_lshl_add_u64 v[50:51], s[6:7], 0, v[96:97]
	v_lshlrev_b32_e32 v96, 2, v8
	v_lshl_add_u64 v[50:51], v[50:51], 0, v[96:97]
	s_mov_b64 s[8:9], 0xc2e4400
	v_lshl_add_u64 v[52:53], v[50:51], 0, s[8:9]
	global_load_dwordx4 v[82:85], v[52:53], off offset:64
	global_load_dwordx4 v[86:89], v[52:53], off offset:128
	s_mov_b32 s8, 0xc2e4000
	v_add_co_u32_e32 v50, vcc, s8, v50
	v_lshlrev_b32_e32 v96, 2, v220
	s_nop 0
	v_addc_co_u32_e32 v51, vcc, 0, v51, vcc
	global_load_dwordx4 v[90:93], v[50:51], off offset:1024
	global_load_dwordx4 v[98:101], v[52:53], off offset:192
	global_load_dwordx4 v[102:105], v[52:53], off offset:256
	global_load_dwordx4 v[106:109], v[52:53], off offset:320
	global_load_dwordx4 v[110:113], v[52:53], off offset:384
	global_load_dwordx4 v[114:117], v[52:53], off offset:448
	v_lshl_add_u64 v[50:51], s[6:7], 0, v[96:97]
	s_mov_b64 s[6:7], 0xc4e4400
	v_lshlrev_b32_e32 v96, 2, v218
	v_lshl_add_u64 v[50:51], v[50:51], 0, s[6:7]
	v_lshl_add_u64 v[52:53], v[50:51], 0, v[96:97]
	v_add_co_u32_e32 v54, vcc, s30, v52
	v_lshlrev_b32_e32 v96, 2, v94
	s_nop 0
	v_addc_co_u32_e32 v55, vcc, 0, v53, vcc
	global_load_dwordx4 v[74:77], v[52:53], off
	global_load_dwordx4 v[70:73], v[52:53], off offset:256
	v_add_co_u32_e32 v52, vcc, s33, v52
	v_lshl_add_u64 v[50:51], v[50:51], 0, v[96:97]
	s_nop 0
	v_addc_co_u32_e32 v53, vcc, 0, v53, vcc
	global_load_dwordx4 v[62:65], v[52:53], off
	global_load_dwordx4 v[58:61], v[52:53], off offset:256
	global_load_dwordx4 v[66:69], v[54:55], off offset:256
	s_nop 0
	global_load_dwordx4 v[54:57], v[50:51], off
	global_load_dwordx4 v[78:81], v[52:53], off offset:-4096
	s_nop 0
	global_load_dwordx4 v[50:53], v[50:51], off offset:256
	v_lshl_add_u32 v94, v8, 2, 0
	v_cmp_le_u32_e32 vcc, v8, v9
	s_waitcnt vmcnt(15)
	v_cvt_pk_bf16_f32 v120, v82, v83
	v_cvt_pk_bf16_f32 v121, v84, v85
	s_waitcnt vmcnt(14)
	v_cvt_pk_bf16_f32 v82, v86, v87
	s_waitcnt vmcnt(13)
	v_cvt_pk_bf16_f32 v118, v90, v91
	v_cvt_pk_bf16_f32 v119, v92, v93
	v_cvt_pk_bf16_f32 v83, v88, v89
	s_waitcnt vmcnt(12)
	v_cvt_pk_bf16_f32 v84, v98, v99
	v_cvt_pk_bf16_f32 v85, v100, v101
	v_mfma_f32_16x16x32_bf16 v[38:41], v[118:121], v[38:41], 0
	s_waitcnt vmcnt(11)
	v_cvt_pk_bf16_f32 v86, v102, v103
	v_cvt_pk_bf16_f32 v87, v104, v105
	s_waitcnt vmcnt(10)
	v_cvt_pk_bf16_f32 v88, v106, v107
	v_cvt_pk_bf16_f32 v89, v108, v109
	v_mfma_f32_16x16x32_bf16 v[38:41], v[82:85], v[42:45], v[38:41]
	s_waitcnt vmcnt(9)
	v_cvt_pk_bf16_f32 v90, v110, v111
	v_cvt_pk_bf16_f32 v91, v112, v113
	s_waitcnt vmcnt(8)
	v_cvt_pk_bf16_f32 v92, v114, v115
	v_cvt_pk_bf16_f32 v93, v116, v117
	v_mfma_f32_16x16x32_bf16 v[38:41], v[86:89], v[46:49], v[38:41]
	ds_read_b128 v[42:45], v94 offset:16384
	v_or_b32_e32 v46, 2, v8
	v_or_b32_e32 v47, 3, v241
	v_mfma_f32_16x16x32_bf16 v[34:37], v[90:93], v[34:37], v[38:41]
	s_waitcnt lgkmcnt(0)
	s_nop 6
	v_fmamk_f32 v34, v34, 0x3e0293ee, v42
	v_fmamk_f32 v35, v35, 0x3e0293ee, v43
	v_cndmask_b32_e32 v96, v232, v34, vcc
	v_cmp_lt_u32_e32 vcc, v8, v9
	v_fmamk_f32 v36, v36, 0x3e0293ee, v44
	v_fmac_f32_e32 v45, 0x3e0293ee, v37
	v_cndmask_b32_e32 v102, v232, v35, vcc
	v_cmp_le_u32_e32 vcc, v46, v9
	s_nop 1
	v_cndmask_b32_e32 v103, v232, v36, vcc
	v_cmp_le_u32_e32 vcc, v47, v9
	s_nop 1
	v_cndmask_b32_e32 v104, v232, v45, vcc
	v_max_f32_e32 v8, v103, v104
	v_max3_f32 v8, v96, v102, v8
	v_mov_b32_e32 v34, v8
	s_nop 1
	v_permlane16_swap_b32_e32 v8, v34
	v_max_f32_e32 v34, v34, v34
	v_max_f32_e32 v8, v8, v8
	v_max_f32_e32 v8, v8, v34
	v_mov_b32_e32 v34, v8
	s_nop 1
	v_permlane32_swap_b32_e32 v8, v34
	v_max3_f32 v94, v242, v8, v34
	v_sub_f32_e32 v8, v242, v94
	v_exp_f32_e32 v8, v8
	s_nop 0
	v_cmp_neq_f32_e32 vcc, 1.0, v8
	s_cbranch_vccz .LBB0_1547
	v_pk_mul_f32 v[36:37], v[24:25], v[8:9] op_sel_hi:[1,0]
	v_pk_mul_f32 v[34:35], v[22:23], v[8:9] op_sel_hi:[1,0]
	v_pk_mul_f32 v[40:41], v[6:7], v[8:9] op_sel_hi:[1,0]
	v_pk_mul_f32 v[38:39], v[4:5], v[8:9] op_sel_hi:[1,0]
	v_pk_mul_f32 v[44:45], v[28:29], v[8:9] op_sel_hi:[1,0]
	v_pk_mul_f32 v[42:43], v[26:27], v[8:9] op_sel_hi:[1,0]
	v_pk_mul_f32 v[48:49], v[32:33], v[8:9] op_sel_hi:[1,0]
	v_pk_mul_f32 v[46:47], v[30:31], v[8:9] op_sel_hi:[1,0]
	v_pk_mul_f32 v[84:85], v[12:13], v[8:9] op_sel_hi:[1,0]
	v_pk_mul_f32 v[82:83], v[10:11], v[8:9] op_sel_hi:[1,0]
	v_pk_mul_f32 v[88:89], v[2:3], v[8:9] op_sel_hi:[1,0]
	v_pk_mul_f32 v[86:87], v[0:1], v[8:9] op_sel_hi:[1,0]
	v_pk_mul_f32 v[92:93], v[16:17], v[8:9] op_sel_hi:[1,0]
	v_pk_mul_f32 v[90:91], v[14:15], v[8:9] op_sel_hi:[1,0]
	v_pk_mul_f32 v[100:101], v[20:21], v[8:9] op_sel_hi:[1,0]
	v_pk_mul_f32 v[98:99], v[18:19], v[8:9] op_sel_hi:[1,0]
	s_cbranch_execnz .LBB0_1014

.LBB0_1072:
	s_or_b64 exec, exec, s[8:9]
	v_readlane_b32 s6, v255, 25
	v_readlane_b32 s7, v255, 26
	s_add_u32 s14, s22, s6
	s_addc_u32 s15, s23, s7
	s_mov_b64 s[6:7], s[0:1]
	s_waitcnt lgkmcnt(0)
	s_barrier
	s_load_dwordx2 s[12:13], s[6:7], 0xb0
	s_add_u32 s8, s14, 0x4200000
	s_addc_u32 s9, s15, 0
	s_add_u32 s6, s14, 0x8220000
	v_readlane_b32 s14, v252, 50
	s_addc_u32 s7, s15, 0
	s_lshl_b32 s14, s14, 1
	v_mov_b32_e32 v86, v219
	s_waitcnt lgkmcnt(0)
	s_add_u32 s12, s12, s14
	s_addc_u32 s13, s13, 0
	v_readfirstlane_b32 s14, v86
	v_and_b32_e32 v87, 15, v86
	s_ashr_i32 s18, s14, 6
	v_lshlrev_b32_e32 v96, 11, v87
	v_lshl_add_u64 v[0:1], s[12:13], 0, v[96:97]
	s_lshl_b32 s12, s18, 1
	v_readlane_b32 s13, v252, 51
	s_add_i32 s14, s12, s13
	s_ashr_i32 s15, s14, 31
	v_lshrrev_b32_e32 v2, 1, v86
	s_lshl_b64 s[20:21], s[14:15], 16
	v_and_b32_e32 v96, 24, v2
	s_add_u32 s12, s6, s20
	v_lshl_add_u64 v[0:1], v[0:1], 0, v[96:97]
	s_addc_u32 s13, s7, s21
	v_lshlrev_b32_e32 v96, 4, v87
	v_lshl_add_u64 v[62:63], s[12:13], 0, v[96:97]
	s_or_b32 s12, s14, 1
	s_ashr_i32 s13, s12, 31
	s_lshl_b64 s[12:13], s[12:13], 16
	v_bfe_u32 v89, v86, 2, 4
	s_add_u32 s20, s8, s20
	v_and_b32_e32 v88, 12, v89
	v_lshlrev_b32_e32 v78, 12, v87
	v_mov_b32_e32 v79, v97
	s_addc_u32 s21, s9, s21
	v_lshl_add_u64 v[74:75], s[6:7], 0, v[96:97]
	v_lshlrev_b32_e32 v96, 2, v88
	v_lshl_add_u64 v[2:3], s[20:21], 0, v[78:79]
	v_lshl_add_u64 v[2:3], v[2:3], 0, v[96:97]
	global_load_dwordx4 v[4:7], v[2:3], off offset:64
	global_load_dwordx4 v[8:11], v[2:3], off
	global_load_dwordx4 v[24:27], v[2:3], off offset:192
	global_load_dwordx4 v[28:31], v[2:3], off offset:128
	s_mov_b64 s[20:21], 0x14a00000
	s_mov_b32 s15, 0x14a00000
	v_lshl_add_u64 v[48:49], v[0:1], 0, s[20:21]
	v_add_co_u32_e32 v0, vcc, s15, v0
	v_mov_b32_e32 v77, v97
	s_nop 0
	v_addc_co_u32_e32 v1, vcc, 0, v1, vcc
	global_load_dwordx4 v[32:35], v[2:3], off offset:256
	global_load_dwordx2 v[20:21], v[0:1], off
	global_load_dwordx2 v[22:23], v[48:49], off offset:32
	global_load_dwordx4 v[36:39], v[2:3], off offset:320
	global_load_dwordx4 v[40:43], v[2:3], off offset:384
	global_load_dwordx2 v[16:17], v[48:49], off offset:64
	global_load_dwordx2 v[18:19], v[48:49], off offset:96
	global_load_dwordx4 v[44:47], v[2:3], off offset:448
	global_load_dwordx2 v[12:13], v[48:49], off offset:128
	global_load_dwordx2 v[14:15], v[48:49], off offset:160
	global_load_dwordx2 v[0:1], v[48:49], off offset:192
	s_nop 0
	global_load_dwordx2 v[2:3], v[48:49], off offset:224
	v_lshlrev_b32_e32 v76, 12, v88
	v_lshl_add_u64 v[64:65], v[62:63], 0, v[76:77]
	global_load_dwordx4 v[48:51], v[64:65], off
	global_load_dwordx4 v[52:55], v[64:65], off offset:256
	v_add_u32_e32 v90, 0, v96
	s_lshl_b32 s14, s14, 6
	s_mov_b32 s15, 0xf149f2ca
	v_mov_b32_e32 v85, v97
	s_movk_i32 s33, 0x2000
	s_waitcnt vmcnt(16)
	v_cvt_pk_bf16_f32 v8, v8, v9
	v_cvt_pk_bf16_f32 v9, v10, v11
	v_cvt_pk_bf16_f32 v10, v4, v5
	v_cvt_pk_bf16_f32 v11, v6, v7
	s_waitcnt vmcnt(14)
	v_cvt_pk_bf16_f32 v4, v28, v29
	v_cvt_pk_bf16_f32 v5, v30, v31
	v_cvt_pk_bf16_f32 v6, v24, v25
	v_cvt_pk_bf16_f32 v7, v26, v27
	s_waitcnt vmcnt(11)
	v_mfma_f32_16x16x32_bf16 v[8:11], v[8:11], v[20:23], 0
	v_cvt_pk_bf16_f32 v24, v32, v33
	v_cvt_pk_bf16_f32 v25, v34, v35
	s_waitcnt vmcnt(10)
	v_cvt_pk_bf16_f32 v26, v36, v37
	v_cvt_pk_bf16_f32 v27, v38, v39
	s_waitcnt vmcnt(7)
	v_mfma_f32_16x16x32_bf16 v[4:7], v[4:7], v[16:19], v[8:11]
	v_cvt_pk_bf16_f32 v28, v40, v41
	v_cvt_pk_bf16_f32 v29, v42, v43
	s_waitcnt vmcnt(6)
	v_cvt_pk_bf16_f32 v30, v44, v45
	v_cvt_pk_bf16_f32 v31, v46, v47
	s_waitcnt vmcnt(4)
	v_mfma_f32_16x16x32_bf16 v[4:7], v[24:27], v[12:15], v[4:7]
	v_add_u32_e32 v8, s14, v90
	ds_read_b128 v[8:11], v8
	s_waitcnt vmcnt(2)
	v_mfma_f32_16x16x32_bf16 v[4:7], v[28:31], v[0:3], v[4:7]
	s_waitcnt lgkmcnt(0)
	s_nop 6
	v_fmamk_f32 v10, v6, 0x3e0293ee, v10
	v_fmac_f32_e32 v11, 0x3e0293ee, v7
	v_fmamk_f32 v4, v4, 0x3e0293ee, v8
	v_fmamk_f32 v32, v5, 0x3e0293ee, v9
	v_max_f32_e32 v5, v10, v11
	v_max3_f32 v5, v4, v32, v5
	v_mov_b32_e32 v6, v5
	s_nop 1
	v_permlane16_swap_b32_e32 v5, v6
	v_max_f32_e32 v6, v6, v6
	v_max_f32_e32 v5, v5, v5
	v_max_f32_e32 v5, v5, v6
	v_mov_b32_e32 v6, v5
	s_nop 1
	v_permlane32_swap_b32_e32 v5, v6
	v_max3_f32 v144, v5, v6, s15
	v_sub_f32_e32 v5, 0xf149f2ca, v144
	v_exp_f32_e32 v5, v5
	v_sub_f32_e32 v4, v4, v144
	v_exp_f32_e32 v92, v4
	s_movk_i32 s15, 0x2000
	v_cmp_neq_f32_e32 vcc, 1.0, v5
	s_cmp_lg_u64 vcc, 0
	v_mul_f32_e32 v33, 0, v5
	s_cselect_b64 vcc, -1, 0
	v_cndmask_b32_e32 v4, 0, v33, vcc
	v_add_co_u32_e32 v8, vcc, s15, v64
	v_mov_b32_e32 v5, v4
	v_mov_b32_e32 v6, v4
	v_mov_b32_e32 v7, v4
	v_addc_co_u32_e32 v9, vcc, 0, v65, vcc
	s_waitcnt vmcnt(1)
	v_mfma_f32_16x16x4_f32 v[24:27], v48, v92, v[4:7]
	v_sub_f32_e32 v32, v32, v144
	v_exp_f32_e32 v93, v32
	global_load_dwordx4 v[58:61], v[8:9], off
	v_mov_b32_e32 v32, 0xc00
	v_lshl_or_b32 v32, v89, 10, v32
	v_lshlrev_b32_e32 v84, 2, v32
	v_lshl_add_u64 v[80:81], v[62:63], 0, v[84:85]
	v_mfma_f32_16x16x4_f32 v[28:31], v49, v92, v[4:7]
	global_load_dwordx4 v[108:111], v[80:81], off offset:256
	global_load_dwordx4 v[66:69], v[8:9], off offset:256
	v_mfma_f32_16x16x4_f32 v[34:37], v50, v92, v[4:7]
	v_mfma_f32_16x16x4_f32 v[38:41], v51, v92, v[4:7]
	s_waitcnt vmcnt(3)
	v_mfma_f32_16x16x4_f32 v[42:45], v52, v92, v[4:7]
	v_mfma_f32_16x16x4_f32 v[46:49], v53, v92, v[4:7]
	v_mfma_f32_16x16x4_f32 v[50:53], v54, v92, v[4:7]
	v_mfma_f32_16x16x4_f32 v[4:7], v55, v92, v[4:7]
	global_load_dwordx4 v[54:57], v[8:9], off offset:-4096
	v_lshl_add_u64 v[8:9], v[74:75], 0, s[12:13]
	v_lshl_add_u64 v[82:83], v[8:9], 0, v[76:77]
	v_lshl_add_u64 v[8:9], v[8:9], 0, v[84:85]
	s_waitcnt vmcnt(0)
	v_mfma_f32_16x16x4_f32 v[24:27], v54, v93, v[24:27]
	v_add_co_u32_e32 v54, vcc, s30, v64
	v_mfma_f32_16x16x4_f32 v[28:31], v55, v93, v[28:31]
	s_nop 0
	v_addc_co_u32_e32 v55, vcc, 0, v65, vcc
	global_load_dwordx4 v[62:65], v[80:81], off
	v_add_co_u32_e32 v98, vcc, s15, v82
	s_nop 1
	v_addc_co_u32_e32 v99, vcc, 0, v83, vcc
	v_mfma_f32_16x16x4_f32 v[34:37], v56, v93, v[34:37]
	v_mfma_f32_16x16x4_f32 v[38:41], v57, v93, v[38:41]
	global_load_dwordx4 v[54:57], v[54:55], off offset:256
	s_waitcnt vmcnt(0)
	v_mfma_f32_16x16x4_f32 v[42:45], v54, v93, v[42:45]
	v_mfma_f32_16x16x4_f32 v[46:49], v55, v93, v[46:49]
	v_mfma_f32_16x16x4_f32 v[50:53], v56, v93, v[50:53]
	v_mfma_f32_16x16x4_f32 v[54:57], v57, v93, v[4:7]
	v_sub_f32_e32 v4, v10, v144
	v_exp_f32_e32 v94, v4
	global_load_dwordx4 v[4:7], v[98:99], off offset:-4096
	v_sub_f32_e32 v10, v11, v144
	v_exp_f32_e32 v95, v10
	v_add_co_u32_e32 v10, vcc, s30, v82
	v_mfma_f32_16x16x4_f32 v[70:73], v61, v94, v[38:41]
	v_lshl_add_u64 v[38:39], s[8:9], 0, v[78:79]
	v_lshl_add_u64 v[38:39], v[38:39], 0, v[96:97]
	v_addc_co_u32_e32 v11, vcc, 0, v83, vcc
	v_mfma_f32_16x16x4_f32 v[74:77], v66, v94, v[42:45]
	v_lshl_add_u64 v[42:43], v[38:39], 0, s[12:13]
	global_load_dwordx4 v[78:81], v[42:43], off
	global_load_dwordx4 v[116:119], v[42:43], off offset:64
	global_load_dwordx4 v[120:123], v[42:43], off offset:128
	global_load_dwordx4 v[124:127], v[42:43], off offset:192
	global_load_dwordx4 v[128:131], v[42:43], off offset:256
	global_load_dwordx4 v[132:135], v[42:43], off offset:320
	global_load_dwordx4 v[136:139], v[42:43], off offset:384
	s_add_i32 s12, s14, 0
	v_add_u32_e32 v32, s12, v96
	v_mfma_f32_16x16x4_f32 v[104:107], v68, v94, v[50:53]
	global_load_dwordx4 v[140:143], v[42:43], off offset:448
	global_load_dwordx4 v[50:53], v[82:83], off
	v_mfma_f32_16x16x4_f32 v[24:27], v58, v94, v[24:27]
	v_mfma_f32_16x16x4_f32 v[28:31], v59, v94, v[28:31]
	v_mfma_f32_16x16x4_f32 v[34:37], v60, v94, v[34:37]
	v_mfma_f32_16x16x4_f32 v[100:103], v67, v94, v[46:49]
	v_mfma_f32_16x16x4_f32 v[112:115], v69, v94, v[54:57]
	v_mfma_f32_16x16x4_f32 v[38:41], v62, v95, v[24:27]
	v_mfma_f32_16x16x4_f32 v[46:49], v63, v95, v[28:31]
	global_load_dwordx4 v[54:57], v[82:83], off offset:256
	global_load_dwordx4 v[42:45], v[10:11], off offset:256
	s_nop 2
	global_load_dwordx4 v[28:31], v[98:99], off
	global_load_dwordx4 v[24:27], v[98:99], off offset:256
	v_mfma_f32_16x16x4_f32 v[58:61], v64, v95, v[34:37]
	global_load_dwordx4 v[34:37], v[8:9], off
	s_nop 0
	global_load_dwordx4 v[8:11], v[8:9], off offset:256
	v_mfma_f32_16x16x4_f32 v[62:65], v65, v95, v[70:73]
	s_waitcnt vmcnt(14)
	v_cvt_pk_bf16_f32 v70, v78, v79
	v_cvt_pk_bf16_f32 v71, v80, v81
	s_waitcnt vmcnt(13)
	v_cvt_pk_bf16_f32 v72, v116, v117
	v_cvt_pk_bf16_f32 v73, v118, v119
	s_waitcnt vmcnt(10)
	v_cvt_pk_bf16_f32 v78, v128, v129
	v_cvt_pk_bf16_f32 v79, v130, v131
	v_mfma_f32_16x16x4_f32 v[66:69], v108, v95, v[74:77]
	v_cvt_pk_bf16_f32 v74, v120, v121
	v_cvt_pk_bf16_f32 v75, v122, v123
	v_cvt_pk_bf16_f32 v76, v124, v125
	v_cvt_pk_bf16_f32 v77, v126, v127
	s_waitcnt vmcnt(9)
	v_cvt_pk_bf16_f32 v80, v132, v133
	v_cvt_pk_bf16_f32 v81, v134, v135
	v_mfma_f32_16x16x32_bf16 v[70:73], v[70:73], v[20:23], 0
	v_mfma_f32_16x16x32_bf16 v[70:73], v[74:77], v[16:19], v[70:73]
	s_waitcnt vmcnt(8)
	v_cvt_pk_bf16_f32 v74, v136, v137
	v_cvt_pk_bf16_f32 v75, v138, v139
	s_waitcnt vmcnt(7)
	v_cvt_pk_bf16_f32 v76, v140, v141
	v_cvt_pk_bf16_f32 v77, v142, v143
	v_mfma_f32_16x16x32_bf16 v[70:73], v[78:81], v[12:15], v[70:73]
	ds_read_b128 v[80:83], v32 offset:64
	v_mfma_f32_16x16x32_bf16 v[70:73], v[74:77], v[0:3], v[70:73]
	s_waitcnt lgkmcnt(0)
	s_nop 6
	v_fmamk_f32 v82, v72, 0x3e0293ee, v82
	v_fmac_f32_e32 v83, 0x3e0293ee, v73
	v_fmamk_f32 v98, v70, 0x3e0293ee, v80
	v_fmamk_f32 v85, v71, 0x3e0293ee, v81
	v_max_f32_e32 v32, v82, v83
	v_max3_f32 v32, v98, v85, v32
	v_mov_b32_e32 v74, v32
	s_nop 1
	v_permlane16_swap_b32_e32 v32, v74
	v_max_f32_e32 v74, v74, v74
	v_max_f32_e32 v32, v32, v32
	v_max_f32_e32 v32, v32, v74
	v_mov_b32_e32 v78, v32
	s_nop 1
	v_permlane32_swap_b32_e32 v32, v78
	v_mfma_f32_16x16x4_f32 v[70:73], v109, v95, v[100:103]
	v_max3_f32 v91, v144, v32, v78
	v_sub_f32_e32 v32, v144, v91
	v_exp_f32_e32 v32, v32
	s_nop 0
	v_cmp_neq_f32_e32 vcc, 1.0, v32
	v_mfma_f32_16x16x4_f32 v[74:77], v110, v95, v[104:107]
	v_mfma_f32_16x16x4_f32 v[78:81], v111, v95, v[112:115]
	s_cbranch_vccz .LBB0_1074
	v_pk_mul_f32 v[40:41], v[40:41], v[32:33] op_sel_hi:[1,0]
	v_pk_mul_f32 v[38:39], v[38:39], v[32:33] op_sel_hi:[1,0]
	v_pk_mul_f32 v[48:49], v[48:49], v[32:33] op_sel_hi:[1,0]
	v_pk_mul_f32 v[46:47], v[46:47], v[32:33] op_sel_hi:[1,0]
	v_pk_mul_f32 v[60:61], v[60:61], v[32:33] op_sel_hi:[1,0]
	v_pk_mul_f32 v[58:59], v[58:59], v[32:33] op_sel_hi:[1,0]
	v_pk_mul_f32 v[64:65], v[64:65], v[32:33] op_sel_hi:[1,0]
	v_pk_mul_f32 v[62:63], v[62:63], v[32:33] op_sel_hi:[1,0]
	v_pk_mul_f32 v[68:69], v[68:69], v[32:33] op_sel_hi:[1,0]
	v_pk_mul_f32 v[66:67], v[66:67], v[32:33] op_sel_hi:[1,0]
	v_pk_mul_f32 v[72:73], v[72:73], v[32:33] op_sel_hi:[1,0]
	v_pk_mul_f32 v[70:71], v[70:71], v[32:33] op_sel_hi:[1,0]
	v_pk_mul_f32 v[76:77], v[76:77], v[32:33] op_sel_hi:[1,0]
	v_pk_mul_f32 v[74:75], v[74:75], v[32:33] op_sel_hi:[1,0]
	v_pk_mul_f32 v[80:81], v[80:81], v[32:33] op_sel_hi:[1,0]
	v_pk_mul_f32 v[78:79], v[78:79], v[32:33] op_sel_hi:[1,0]
.LBB0_1074:
	v_add_f32_e32 v92, v92, v93
	v_add_f32_e32 v93, v94, v95
	v_add_f32_e32 v92, v92, v93
	v_add_f32_e32 v33, v33, v92
	v_sub_f32_e32 v92, v98, v91
	v_exp_f32_e32 v92, v92
	v_sub_f32_e32 v85, v85, v91
	v_exp_f32_e32 v85, v85
	s_waitcnt vmcnt(6)
	v_mfma_f32_16x16x4_f32 v[38:41], v50, v92, v[38:41]
	v_sub_f32_e32 v82, v82, v91
	v_exp_f32_e32 v93, v82
	v_sub_f32_e32 v82, v83, v91
	v_exp_f32_e32 v83, v82
	v_add_f32_e32 v82, v92, v85
	s_cmp_eq_u32 s18, 7
	v_readlane_b32 s14, v252, 52
	v_mfma_f32_16x16x4_f32 v[46:49], v51, v92, v[46:49]
	v_add_f32_e32 v94, v93, v83
	v_add_f32_e32 v82, v82, v94
	v_fmac_f32_e32 v82, v33, v32
	s_cselect_b64 s[12:13], -1, 0
	v_readlane_b32 s15, v252, 53
	s_and_b64 s[12:13], s[14:15], s[12:13]
	s_andn2_b64 vcc, exec, s[12:13]
	v_mfma_f32_16x16x4_f32 v[58:61], v52, v92, v[58:61]
	v_mfma_f32_16x16x4_f32 v[50:53], v53, v92, v[62:65]
	s_waitcnt vmcnt(5)
	v_mfma_f32_16x16x4_f32 v[62:65], v54, v92, v[66:69]
	v_mfma_f32_16x16x4_f32 v[66:69], v55, v92, v[70:73]
	v_mfma_f32_16x16x4_f32 v[70:73], v56, v92, v[74:77]
	v_mfma_f32_16x16x4_f32 v[54:57], v57, v92, v[78:81]
	v_mfma_f32_16x16x4_f32 v[38:41], v4, v85, v[38:41]
	v_mfma_f32_16x16x4_f32 v[46:49], v5, v85, v[46:49]
	v_mfma_f32_16x16x4_f32 v[58:61], v6, v85, v[58:61]
	v_mfma_f32_16x16x4_f32 v[4:7], v7, v85, v[50:53]
	s_waitcnt vmcnt(4)
	v_mfma_f32_16x16x4_f32 v[50:53], v42, v85, v[62:65]
	v_mfma_f32_16x16x4_f32 v[62:65], v43, v85, v[66:69]
	v_mfma_f32_16x16x4_f32 v[66:69], v44, v85, v[70:73]
	v_mfma_f32_16x16x4_f32 v[42:45], v45, v85, v[54:57]
	s_waitcnt vmcnt(3)
	v_mfma_f32_16x16x4_f32 v[38:41], v28, v93, v[38:41]
	v_mfma_f32_16x16x4_f32 v[46:49], v29, v93, v[46:49]
	v_mfma_f32_16x16x4_f32 v[54:57], v30, v93, v[58:61]
	v_mfma_f32_16x16x4_f32 v[4:7], v31, v93, v[4:7]
	s_waitcnt vmcnt(2)
	v_mfma_f32_16x16x4_f32 v[50:53], v24, v93, v[50:53]
	v_mfma_f32_16x16x4_f32 v[58:61], v25, v93, v[62:65]
	v_mfma_f32_16x16x4_f32 v[62:65], v26, v93, v[66:69]
	v_mfma_f32_16x16x4_f32 v[66:69], v27, v93, v[42:45]
	s_waitcnt vmcnt(1)
	v_mfma_f32_16x16x4_f32 v[24:27], v34, v83, v[38:41]
	v_mfma_f32_16x16x4_f32 v[28:31], v35, v83, v[46:49]
	v_mfma_f32_16x16x4_f32 v[32:35], v36, v83, v[54:57]
	v_mfma_f32_16x16x4_f32 v[4:7], v37, v83, v[4:7]
	s_waitcnt vmcnt(0)
	v_mfma_f32_16x16x4_f32 v[36:39], v8, v83, v[50:53]
	v_mfma_f32_16x16x4_f32 v[40:43], v9, v83, v[58:61]
	v_mfma_f32_16x16x4_f32 v[44:47], v10, v83, v[62:65]
	v_mfma_f32_16x16x4_f32 v[8:11], v11, v83, v[66:69]
	s_cbranch_vccnz .LBB0_1089
	v_lshlrev_b32_e32 v48, 10, v87
	v_lshlrev_b32_e32 v48, 2, v48
	v_mov_b32_e32 v49, v97
	v_lshl_add_u64 v[48:49], s[8:9], 0, v[48:49]
	v_lshl_add_u64 v[48:49], v[48:49], 0, v[96:97]
	s_mov_b64 s[8:9], 0x2000000
	v_lshl_add_u64 v[50:51], v[48:49], 0, s[8:9]
	global_load_dwordx4 v[92:95], v[50:51], off offset:64
	global_load_dwordx4 v[98:101], v[50:51], off offset:128
	v_add_co_u32_e32 v48, vcc, 0x2000000, v48
	v_mov_b32_e32 v85, v97
	s_nop 0
	v_addc_co_u32_e32 v49, vcc, 0, v49, vcc
	global_load_dwordx4 v[102:105], v[48:49], off
	global_load_dwordx4 v[106:109], v[50:51], off offset:192
	global_load_dwordx4 v[110:113], v[50:51], off offset:256
	global_load_dwordx4 v[114:117], v[50:51], off offset:320
	global_load_dwordx4 v[118:121], v[50:51], off offset:384
	global_load_dwordx4 v[122:125], v[50:51], off offset:448
	v_lshlrev_b32_e32 v48, 2, v87
	v_lshlrev_b32_e32 v96, 2, v48
	v_lshlrev_b32_e32 v50, 10, v88
	v_lshl_add_u64 v[48:49], s[6:7], 0, v[96:97]
	v_lshlrev_b32_e32 v96, 2, v50
	v_lshl_add_u64 v[48:49], v[48:49], 0, s[8:9]
	v_lshl_add_u64 v[50:51], v[48:49], 0, v[96:97]
	v_add_co_u32_e32 v52, vcc, s30, v50
	global_load_dwordx4 v[76:79], v[50:51], off
	global_load_dwordx4 v[68:71], v[50:51], off offset:256
	v_addc_co_u32_e32 v53, vcc, 0, v51, vcc
	v_add_co_u32_e32 v50, vcc, s33, v50
	v_lshl_add_u64 v[48:49], v[48:49], 0, v[84:85]
	s_nop 0
	v_addc_co_u32_e32 v51, vcc, 0, v51, vcc
	global_load_dwordx4 v[60:63], v[50:51], off
	global_load_dwordx4 v[56:59], v[50:51], off offset:256
	global_load_dwordx4 v[64:67], v[52:53], off offset:256
	s_nop 0
	global_load_dwordx4 v[52:55], v[48:49], off
	global_load_dwordx4 v[72:75], v[50:51], off offset:-4096
	s_nop 0
	global_load_dwordx4 v[48:51], v[48:49], off offset:256
	v_cmp_le_u32_e32 vcc, v88, v87
	s_waitcnt vmcnt(15)
	v_cvt_pk_bf16_f32 v128, v92, v93
	v_cvt_pk_bf16_f32 v129, v94, v95
	s_waitcnt vmcnt(13)
	v_cvt_pk_bf16_f32 v126, v102, v103
	v_cvt_pk_bf16_f32 v127, v104, v105
	v_cvt_pk_bf16_f32 v92, v98, v99
	v_cvt_pk_bf16_f32 v93, v100, v101
	s_waitcnt vmcnt(12)
	v_cvt_pk_bf16_f32 v94, v106, v107
	v_cvt_pk_bf16_f32 v95, v108, v109
	v_mfma_f32_16x16x32_bf16 v[20:23], v[126:129], v[20:23], 0
	s_waitcnt vmcnt(11)
	v_cvt_pk_bf16_f32 v98, v110, v111
	v_cvt_pk_bf16_f32 v99, v112, v113
	s_waitcnt vmcnt(10)
	v_cvt_pk_bf16_f32 v100, v114, v115
	v_cvt_pk_bf16_f32 v101, v116, v117
	v_mfma_f32_16x16x32_bf16 v[16:19], v[92:95], v[16:19], v[20:23]
	s_waitcnt vmcnt(9)
	v_cvt_pk_bf16_f32 v102, v118, v119
	v_cvt_pk_bf16_f32 v103, v120, v121
	s_waitcnt vmcnt(8)
	v_cvt_pk_bf16_f32 v104, v122, v123
	v_cvt_pk_bf16_f32 v105, v124, v125
	v_mfma_f32_16x16x32_bf16 v[12:15], v[98:101], v[12:15], v[16:19]
	v_or_b32_e32 v20, 2, v88
	v_or_b32_e32 v21, 3, v89
	s_nop 0
	ds_read_b128 v[16:19], v90 offset:32768
	v_mfma_f32_16x16x32_bf16 v[0:3], v[102:105], v[0:3], v[12:15]
	s_waitcnt lgkmcnt(0)
	s_nop 6
	v_fmamk_f32 v0, v0, 0x3e0293ee, v16
	v_fmamk_f32 v12, v1, 0x3e0293ee, v17
	v_cndmask_b32_e32 v1, v232, v0, vcc
	v_cmp_lt_u32_e32 vcc, v88, v87
	v_fmamk_f32 v13, v2, 0x3e0293ee, v18
	v_fmac_f32_e32 v19, 0x3e0293ee, v3
	v_cndmask_b32_e32 v2, v232, v12, vcc
	v_cmp_le_u32_e32 vcc, v20, v87
	s_nop 1
	v_cndmask_b32_e32 v3, v232, v13, vcc
	v_cmp_le_u32_e32 vcc, v21, v87
	s_nop 1
	v_cndmask_b32_e32 v12, v232, v19, vcc
	v_max_f32_e32 v0, v3, v12
	v_max3_f32 v0, v1, v2, v0
	v_mov_b32_e32 v13, v0
	s_nop 1
	v_permlane16_swap_b32_e32 v0, v13
	v_max_f32_e32 v13, v13, v13
	v_max_f32_e32 v0, v0, v0
	v_max_f32_e32 v0, v0, v13
	v_mov_b32_e32 v13, v0
	s_nop 1
	v_permlane32_swap_b32_e32 v0, v13
	v_max3_f32 v80, v91, v0, v13
	v_sub_f32_e32 v0, v91, v80
	v_exp_f32_e32 v0, v0
	s_nop 0
	v_cmp_neq_f32_e32 vcc, 1.0, v0
	s_cbranch_vccz .LBB0_1077
	v_pk_mul_f32 v[26:27], v[26:27], v[0:1] op_sel_hi:[1,0]
	v_pk_mul_f32 v[24:25], v[24:25], v[0:1] op_sel_hi:[1,0]
	v_pk_mul_f32 v[30:31], v[30:31], v[0:1] op_sel_hi:[1,0]
	v_pk_mul_f32 v[28:29], v[28:29], v[0:1] op_sel_hi:[1,0]
	v_pk_mul_f32 v[34:35], v[34:35], v[0:1] op_sel_hi:[1,0]
	v_pk_mul_f32 v[32:33], v[32:33], v[0:1] op_sel_hi:[1,0]
	v_pk_mul_f32 v[6:7], v[6:7], v[0:1] op_sel_hi:[1,0]
	v_pk_mul_f32 v[4:5], v[4:5], v[0:1] op_sel_hi:[1,0]
	v_pk_mul_f32 v[38:39], v[38:39], v[0:1] op_sel_hi:[1,0]
	v_pk_mul_f32 v[36:37], v[36:37], v[0:1] op_sel_hi:[1,0]
	v_pk_mul_f32 v[42:43], v[42:43], v[0:1] op_sel_hi:[1,0]
	v_pk_mul_f32 v[40:41], v[40:41], v[0:1] op_sel_hi:[1,0]
	v_pk_mul_f32 v[46:47], v[46:47], v[0:1] op_sel_hi:[1,0]
	v_pk_mul_f32 v[44:45], v[44:45], v[0:1] op_sel_hi:[1,0]
	v_pk_mul_f32 v[10:11], v[10:11], v[0:1] op_sel_hi:[1,0]
	v_pk_mul_f32 v[8:9], v[8:9], v[0:1] op_sel_hi:[1,0]
